# W2 third round split along K over all 256 workgroups: partial accumulators via write-through stores + one arrival per producer workgroup, owner wave 0 polls then reduces in fixed order
# speedup vs baseline: 1.0123x; 1.0087x over previous
.LBB0_85:
	s_mul_i32 s17, s14, 0x36000
	s_sext_i32_i8 s84, s4
	s_mul_hi_i32 s4, s14, 0x36000
	s_add_u32 s17, s76, s17
	v_writelane_b32 v255, s76, 34
	s_addc_u32 s4, s77, s4
	s_add_u32 s72, s17, 0x5000
	s_addc_u32 s73, s4, 0
	v_and_b32_e32 v15, 15, v145
	s_add_i32 s74, s64, 0x18000
	v_writelane_b32 v255, s77, 35
	v_bfe_u32 v14, v145, 4, 2
	v_lshlrev_b32_e32 v16, 6, v15
	v_lshlrev_b32_e32 v17, 2, v145
	s_add_i32 s77, s74, s10
	v_lshl_or_b32 v16, v14, 4, v16
	v_and_b32_e32 v17, 32, v17
	s_and_b32 s24, s16, 3
	s_lshl_b32 s4, s11, 13
	v_lshl_add_u64 v[6:7], v[6:7], 0, s[8:9]
	s_mov_b32 m0, s77
	s_add_i32 s78, s77, 0x2000
	s_add_i32 s75, s64, 0x1c000
	s_ashr_i32 s76, s44, 31
	v_lshl_or_b32 v178, s11, 6, v15
	v_bitop3_b32 v15, v16, s4, v17 bitop3:0xde
	s_lshl_b32 s4, s24, 12
	s_waitcnt vmcnt(2)
	s_barrier
	global_load_lds_dwordx4 v[6:7], off
	v_lshl_add_u64 v[4:5], v[4:5], 0, s[8:9]
	s_mov_b32 m0, s78
	s_add_i32 s79, s47, 0x8000
	s_add_i32 s80, s47, 0xa000
	global_load_lds_dwordx4 v[4:5], off
	v_lshl_add_u64 v[0:1], v[0:1], 0, s[8:9]
	s_mov_b32 m0, s79
	s_add_u32 s16, s56, 0x40080
	global_load_lds_dwordx4 v[0:1], off
	v_lshl_add_u64 v[0:1], v[2:3], 0, s[8:9]
	s_mov_b32 m0, s80
	s_addc_u32 s17, s57, 0
	s_add_i32 s81, s75, s10
	global_load_lds_dwordx4 v[0:1], off
	v_lshl_add_u64 v[0:1], s[16:17], 0, v[148:149]
	s_mov_b32 m0, s81
	s_add_i32 s82, s81, 0x2000
	global_load_lds_dwordx4 v[0:1], off
	v_lshl_add_u64 v[0:1], s[16:17], 0, v[166:167]
	s_mov_b32 m0, s82
	v_lshlrev_b32_e32 v14, 2, v14
	global_load_lds_dwordx4 v[0:1], off
	v_lshlrev_b32_e32 v0, 16, v8
	v_and_b32_e32 v0, 0xfffe0000, v0
	v_lshl_add_u32 v0, v9, 13, v0
	v_and_b32_e32 v1, 1, v8
	v_lshl_or_b32 v0, v1, 6, v0
	v_lshl_add_u32 v168, v10, 1, v0
	v_lshlrev_b32_e32 v0, 16, v11
	v_and_b32_e32 v0, 0xfffe0000, v0
	s_waitcnt vmcnt(6)
	v_lshl_add_u32 v0, v12, 13, v0
	v_and_b32_e32 v1, 1, v11
	s_cmpk_lt_u32 s5, 0x100
	v_lshl_or_b32 v0, v1, 6, v0
	v_bitop3_b32 v179, s4, v16, v17 bitop3:0xf6
	s_cselect_b64 s[4:5], -1, 0
	v_lshl_or_b32 v180, s24, 6, v14
	v_mov_b32_e32 v169, v149
	v_lshl_add_u32 v170, v13, 1, v0
	v_mov_b32_e32 v171, v149
	s_mov_b32 s83, 0
	s_mov_b32 s32, 0
	v_add_u32_e32 v181, s64, v15
	s_barrier
	s_branch .LBB0_89

.LBB0_88:
	s_andn2_b64 vcc, exec, s[16:17]
	s_mov_b32 s32, s40
	s_mov_b32 s84, s10
	s_mov_b32 s46, s24
	s_mov_b64 s[56:57], s[28:29]
	s_mov_b64 s[48:49], s[26:27]
	s_cbranch_vccz .LBB0_100
.LBB0_89:
	s_add_i32 s83, s83, 1
	s_mov_b32 s40, 0
	s_cmp_lg_u32 s44, 0x100
	s_cbranch_scc1 .Lsk_sched_orig
	s_lshl_b32 s16, s83, 8
	s_add_i32 s16, s16, s42
	s_cmp_lt_u32 s83, 3
	s_cselect_b64 s[38:39], -1, 0
	s_cbranch_scc0 .LBB0_91
	s_cmp_lt_u32 s83, 2
	s_cbranch_scc1 .Lsk_map
	s_and_b32 s16, s42, 63
	s_addk_i32 s16, 0x200
	s_lshr_b32 s40, s42, 6
	s_or_b32 s40, s40, 8
	s_branch .Lsk_map
.Lsk_sched_orig:
	s_mul_i32 s11, s83, s76
	s_mul_hi_u32 s16, s83, s44
	s_add_i32 s11, s16, s11
	s_mul_i32 s16, s83, s44
	s_add_u32 s16, s16, s42
	s_addc_u32 s17, s11, s33
	v_cmp_gt_i64_e32 vcc, s[16:17], v[154:155]
	v_cmp_lt_i64_e64 s[38:39], s[16:17], v[152:153]
	s_cbranch_vccnz .LBB0_91
.Lsk_map:
	s_ashr_i32 s10, s16, 31
	s_lshr_b32 s10, s10, 29
	s_add_i32 s10, s16, s10
	s_ashr_i32 s11, s10, 3
	s_and_b32 s10, s10, -8
	s_sub_i32 s10, s16, s10
	s_cmp_lt_i32 s10, 0
	s_movk_i32 s16, 0x49
	s_cselect_b32 s16, s16, 0x48
	s_mul_i32 s10, s10, s16
	s_add_i32 s10, s10, s11
	s_ashr_i32 s11, s10, 31
	s_lshr_b32 s11, s11, 29
	s_add_i32 s11, s10, s11
	s_ashr_i32 s16, s11, 3
	s_lshl_b32 s16, s16, 1
	s_sub_i32 s17, 0x90, s16
	s_min_i32 s17, s17, 2
	s_abs_i32 s24, s17
	v_cvt_f32_u32_e32 v0, s24
	s_sub_i32 s26, 0, s24
	s_and_b32 s11, s11, -8
	s_sub_i32 s11, s10, s11
	v_rcp_iflag_f32_e32 v0, v0
	s_abs_i32 s10, s11
	s_xor_b32 s25, s11, s17
	s_ashr_i32 s25, s25, 31
	v_mul_f32_e32 v0, 0x4f7ffffe, v0
	v_cvt_u32_f32_e32 v0, v0
	s_nop 0
	v_readfirstlane_b32 s27, v0
	s_mul_i32 s26, s26, s27
	s_mul_hi_u32 s26, s27, s26
	s_add_i32 s27, s27, s26
	s_mul_hi_u32 s26, s10, s27
	s_mul_i32 s27, s26, s24
	s_sub_i32 s10, s10, s27
	s_add_i32 s28, s26, 1
	s_sub_i32 s27, s10, s24
	s_cmp_ge_u32 s10, s24
	s_cselect_b32 s26, s28, s26
	s_cselect_b32 s10, s27, s10
	s_add_i32 s27, s26, 1
	s_cmp_ge_u32 s10, s24
	s_cselect_b32 s10, s27, s26
	s_xor_b32 s10, s10, s25
	s_sub_i32 s10, s10, s25
	s_mul_i32 s17, s10, s17
	s_sub_i32 s11, s11, s17
	s_add_i32 s24, s16, s11
.LBB0_91:
	s_ashr_i32 s25, s24, 31
	s_lshl_b64 s[16:17], s[24:25], 21
	s_add_u32 s26, s18, s16
	s_addc_u32 s27, s19, s17
	s_and_b32 s41, s40, 3
	s_lshl_b32 s41, s41, 11
	s_add_u32 s26, s26, s41
	s_addc_u32 s27, s27, 0
	s_and_b64 s[16:17], s[38:39], exec
	s_cselect_b32 s25, s27, s49
	s_cselect_b32 s85, s26, s48
	s_ashr_i32 s11, s10, 31
	s_lshl_b64 s[16:17], s[10:11], 21
	s_add_u32 s28, s20, s16
	s_addc_u32 s29, s21, s17
	s_add_u32 s28, s28, s41
	s_addc_u32 s29, s29, 0
	s_and_b64 s[16:17], s[38:39], exec
	s_cselect_b32 s11, s29, s57
	s_cselect_b32 s86, s28, s56
	s_add_u32 s48, s48, 0x100080
	s_addc_u32 s49, s49, 0
	s_add_u32 s87, s56, 0x100
	v_mov_b32_e32 v0, 0
	s_addc_u32 s88, s57, 0
	s_cmp_eq_u32 s32, 0
	s_cselect_b32 s89, -2, 46
	v_mov_b32_e32 v1, v0
	v_mov_b32_e32 v2, v0
	v_mov_b32_e32 v3, v0
	v_mov_b32_e32 v4, v0
	v_mov_b32_e32 v5, v0
	v_mov_b32_e32 v6, v0
	v_mov_b32_e32 v7, v0
	v_mov_b32_e32 v16, v0
	v_mov_b32_e32 v17, v0
	v_mov_b32_e32 v18, v0
	v_mov_b32_e32 v19, v0
	v_mov_b32_e32 v20, v0
	v_mov_b32_e32 v21, v0
	v_mov_b32_e32 v22, v0
	v_mov_b32_e32 v23, v0
	v_mov_b32_e32 v32, v0
	v_mov_b32_e32 v33, v0
	v_mov_b32_e32 v34, v0
	v_mov_b32_e32 v35, v0
	v_mov_b32_e32 v36, v0
	v_mov_b32_e32 v37, v0
	v_mov_b32_e32 v38, v0
	v_mov_b32_e32 v39, v0
	v_mov_b32_e32 v48, v0
	v_mov_b32_e32 v49, v0
	v_mov_b32_e32 v50, v0
	v_mov_b32_e32 v51, v0
	v_mov_b32_e32 v52, v0
	v_mov_b32_e32 v53, v0
	v_mov_b32_e32 v54, v0
	v_mov_b32_e32 v55, v0
	v_mov_b32_e32 v8, v0
	v_mov_b32_e32 v9, v0
	v_mov_b32_e32 v10, v0
	v_mov_b32_e32 v11, v0
	v_mov_b32_e32 v12, v0
	v_mov_b32_e32 v13, v0
	v_mov_b32_e32 v14, v0
	v_mov_b32_e32 v15, v0
	v_mov_b32_e32 v24, v0
	v_mov_b32_e32 v25, v0
	v_mov_b32_e32 v26, v0
	v_mov_b32_e32 v27, v0
	v_mov_b32_e32 v28, v0
	v_mov_b32_e32 v29, v0
	v_mov_b32_e32 v30, v0
	v_mov_b32_e32 v31, v0
	v_mov_b32_e32 v40, v0
	v_mov_b32_e32 v41, v0
	v_mov_b32_e32 v42, v0
	v_mov_b32_e32 v43, v0
	v_mov_b32_e32 v44, v0
	v_mov_b32_e32 v45, v0
	v_mov_b32_e32 v46, v0
	v_mov_b32_e32 v47, v0
	v_mov_b32_e32 v56, v0
	v_mov_b32_e32 v57, v0
	v_mov_b32_e32 v58, v0
	v_mov_b32_e32 v59, v0
	v_mov_b32_e32 v60, v0
	v_mov_b32_e32 v61, v0
	v_mov_b32_e32 v62, v0
	v_mov_b32_e32 v63, v0
	v_mov_b32_e32 v64, v0
	v_mov_b32_e32 v65, v0
	v_mov_b32_e32 v66, v0
	v_mov_b32_e32 v67, v0
	v_mov_b32_e32 v68, v0
	v_mov_b32_e32 v69, v0
	v_mov_b32_e32 v70, v0
	v_mov_b32_e32 v71, v0
	v_mov_b32_e32 v92, v0
	v_mov_b32_e32 v93, v0
	v_mov_b32_e32 v94, v0
	v_mov_b32_e32 v95, v0
	v_mov_b32_e32 v100, v0
	v_mov_b32_e32 v101, v0
	v_mov_b32_e32 v102, v0
	v_mov_b32_e32 v103, v0
	v_mov_b32_e32 v112, v0
	v_mov_b32_e32 v113, v0
	v_mov_b32_e32 v114, v0
	v_mov_b32_e32 v115, v0
	v_mov_b32_e32 v116, v0
	v_mov_b32_e32 v117, v0
	v_mov_b32_e32 v118, v0
	v_mov_b32_e32 v119, v0
	v_mov_b32_e32 v128, v0
	v_mov_b32_e32 v129, v0
	v_mov_b32_e32 v130, v0
	v_mov_b32_e32 v131, v0
	v_mov_b32_e32 v132, v0
	v_mov_b32_e32 v133, v0
	v_mov_b32_e32 v134, v0
	v_mov_b32_e32 v135, v0
	v_mov_b32_e32 v72, v0
	v_mov_b32_e32 v73, v0
	v_mov_b32_e32 v74, v0
	v_mov_b32_e32 v75, v0
	v_mov_b32_e32 v80, v0
	v_mov_b32_e32 v81, v0
	v_mov_b32_e32 v82, v0
	v_mov_b32_e32 v83, v0
	v_mov_b32_e32 v104, v0
	v_mov_b32_e32 v105, v0
	v_mov_b32_e32 v106, v0
	v_mov_b32_e32 v107, v0
	v_mov_b32_e32 v108, v0
	v_mov_b32_e32 v109, v0
	v_mov_b32_e32 v110, v0
	v_mov_b32_e32 v111, v0
	v_mov_b32_e32 v120, v0
	v_mov_b32_e32 v121, v0
	v_mov_b32_e32 v122, v0
	v_mov_b32_e32 v123, v0
	v_mov_b32_e32 v124, v0
	v_mov_b32_e32 v125, v0
	v_mov_b32_e32 v126, v0
	v_mov_b32_e32 v127, v0
	v_mov_b32_e32 v136, v0
	v_mov_b32_e32 v137, v0
	v_mov_b32_e32 v138, v0
	v_mov_b32_e32 v139, v0
	v_mov_b32_e32 v140, v0
	v_mov_b32_e32 v141, v0
	v_mov_b32_e32 v142, v0
	v_mov_b32_e32 v143, v0

.LBB0_95:
	s_cmp_eq_u32 s32, 0
	s_cbranch_scc1 .Lsk_full
	v_lshlrev_b32_e32 v189, 4, v145
	s_and_b32 s41, s42, 63
	s_cmp_eq_u32 s32, 8
	s_cbranch_scc1 .Lsk_owner
	s_mul_i32 s16, s41, 3
	s_and_b32 s17, s32, 3
	s_add_i32 s16, s16, s17
	s_add_i32 s16, s16, -1
	s_lshl_b32 s16, s16, 3
	s_add_i32 s16, s16, s65
	s_lshl_b32 s16, s16, 15
	s_add_u32 s16, s54, s16
	s_addc_u32 s17, s55, 0
	s_add_u32 s16, s16, 0x2800000
	s_addc_u32 s17, s17, 0
	global_store_dwordx4 v189, v[140:143], s[16:17] sc1
	global_store_dwordx4 v189, v[136:139], s[16:17] offset:1024 sc1
	global_store_dwordx4 v189, v[132:135], s[16:17] offset:2048 sc1
	global_store_dwordx4 v189, v[128:131], s[16:17] offset:3072 sc1
	s_add_u32 s16, s16, 0x1000
	s_addc_u32 s17, s17, 0
	s_nop 0
	global_store_dwordx4 v189, v[124:127], s[16:17] sc1
	global_store_dwordx4 v189, v[120:123], s[16:17] offset:1024 sc1
	global_store_dwordx4 v189, v[116:119], s[16:17] offset:2048 sc1
	global_store_dwordx4 v189, v[112:115], s[16:17] offset:3072 sc1
	s_add_u32 s16, s16, 0x1000
	s_addc_u32 s17, s17, 0
	s_nop 0
	global_store_dwordx4 v189, v[108:111], s[16:17] sc1
	global_store_dwordx4 v189, v[104:107], s[16:17] offset:1024 sc1
	global_store_dwordx4 v189, v[100:103], s[16:17] offset:2048 sc1
	global_store_dwordx4 v189, v[92:95], s[16:17] offset:3072 sc1
	s_add_u32 s16, s16, 0x1000
	s_addc_u32 s17, s17, 0
	s_nop 0
	global_store_dwordx4 v189, v[80:83], s[16:17] sc1
	global_store_dwordx4 v189, v[72:75], s[16:17] offset:1024 sc1
	global_store_dwordx4 v189, v[68:71], s[16:17] offset:2048 sc1
	global_store_dwordx4 v189, v[64:67], s[16:17] offset:3072 sc1
	s_add_u32 s16, s16, 0x1000
	s_addc_u32 s17, s17, 0
	s_nop 0
	global_store_dwordx4 v189, v[60:63], s[16:17] sc1
	global_store_dwordx4 v189, v[56:59], s[16:17] offset:1024 sc1
	global_store_dwordx4 v189, v[52:55], s[16:17] offset:2048 sc1
	global_store_dwordx4 v189, v[48:51], s[16:17] offset:3072 sc1
	s_add_u32 s16, s16, 0x1000
	s_addc_u32 s17, s17, 0
	s_nop 0
	global_store_dwordx4 v189, v[44:47], s[16:17] sc1
	global_store_dwordx4 v189, v[40:43], s[16:17] offset:1024 sc1
	global_store_dwordx4 v189, v[36:39], s[16:17] offset:2048 sc1
	global_store_dwordx4 v189, v[32:35], s[16:17] offset:3072 sc1
	s_add_u32 s16, s16, 0x1000
	s_addc_u32 s17, s17, 0
	s_nop 0
	global_store_dwordx4 v189, v[28:31], s[16:17] sc1
	global_store_dwordx4 v189, v[24:27], s[16:17] offset:1024 sc1
	global_store_dwordx4 v189, v[20:23], s[16:17] offset:2048 sc1
	global_store_dwordx4 v189, v[16:19], s[16:17] offset:3072 sc1
	s_add_u32 s16, s16, 0x1000
	s_addc_u32 s17, s17, 0
	s_nop 0
	global_store_dwordx4 v189, v[12:15], s[16:17] sc1
	global_store_dwordx4 v189, v[8:11], s[16:17] offset:1024 sc1
	global_store_dwordx4 v189, v[4:7], s[16:17] offset:2048 sc1
	global_store_dwordx4 v189, v[0:3], s[16:17] offset:3072 sc1
	s_lshl_b32 s41, s41, 2
	s_add_u32 s90, s54, s41
	s_addc_u32 s91, s55, 0
	s_add_u32 s90, s90, 0xf0000
	s_addc_u32 s91, s91, 0
	v_mov_b32_e32 v190, 1
	s_waitcnt vmcnt(0)
	s_barrier
	s_cmp_lg_u32 s65, 0
	s_cbranch_scc1 .Lsk_nosig
	s_mov_b64 s[88:89], exec
	s_mov_b64 exec, 1
	global_atomic_add v149, v190, s[90:91]
	s_mov_b64 exec, s[88:89]
.Lsk_nosig:
	s_mov_b32 s91, 0xa0000
	s_mov_b64 s[88:89], 0xc80800
	s_mov_b32 s11, 0xb0000
	s_mov_b64 s[16:17], -1
	s_branch .LBB0_88
.Lsk_owner:
	s_lshl_b32 s16, s41, 2
	s_add_u32 s90, s54, s16
	s_addc_u32 s91, s55, 0
	s_add_u32 s90, s90, 0xf0000
	s_addc_u32 s91, s91, 0
	s_mul_i32 s11, s14, 3
	s_add_i32 s11, s11, 3
	s_mov_b32 s89, 0
	s_cmp_lg_u32 s65, 0
	s_cbranch_scc1 .Lsk_got
.Lsk_poll:
	global_load_dword v190, v149, s[90:91] sc1
	s_waitcnt vmcnt(0)
	v_readfirstlane_b32 s16, v190
	s_cmp_ge_u32 s16, s11
	s_cbranch_scc1 .Lsk_got
	s_sleep 16
	s_add_i32 s89, s89, 1
	s_cmp_lt_u32 s89, 0x4000
	s_cbranch_scc1 .Lsk_poll
.Lsk_got:
	s_barrier
	buffer_inv sc1
	s_mul_i32 s16, s41, 24
	s_add_i32 s16, s16, s65
	s_lshl_b32 s16, s16, 15
	s_add_u32 s16, s54, s16
	s_addc_u32 s17, s55, 0
	s_add_u32 s16, s16, 0x2800000
	s_addc_u32 s17, s17, 0
	s_add_u32 s88, s16, 0x40000
	s_addc_u32 s89, s17, 0
	s_add_u32 s90, s16, 0x80000
	s_addc_u32 s91, s17, 0
	global_load_dwordx4 v[192:195], v189, s[16:17]
	global_load_dwordx4 v[196:199], v189, s[88:89]
	global_load_dwordx4 v[200:203], v189, s[90:91]
	global_load_dwordx4 v[204:207], v189, s[16:17] offset:1024
	global_load_dwordx4 v[208:211], v189, s[88:89] offset:1024
	global_load_dwordx4 v[212:215], v189, s[90:91] offset:1024
	global_load_dwordx4 v[216:219], v189, s[16:17] offset:2048
	global_load_dwordx4 v[220:223], v189, s[88:89] offset:2048
	global_load_dwordx4 v[224:227], v189, s[90:91] offset:2048
	global_load_dwordx4 v[228:231], v189, s[16:17] offset:3072
	global_load_dwordx4 v[232:235], v189, s[88:89] offset:3072
	global_load_dwordx4 v[84:87], v189, s[90:91] offset:3072
	s_add_u32 s16, s16, 0x1000
	s_addc_u32 s17, s17, 0
	s_add_u32 s88, s88, 0x1000
	s_addc_u32 s89, s89, 0
	s_add_u32 s90, s90, 0x1000
	s_addc_u32 s91, s91, 0
	global_load_dwordx4 v[88:91], v189, s[16:17]
	global_load_dwordx4 v[76:79], v189, s[88:89]
	global_load_dwordx4 v[96:99], v189, s[90:91]
	s_waitcnt vmcnt(14)
	v_pk_add_f32 v[140:141], v[140:141], v[192:193]
	v_pk_add_f32 v[142:143], v[142:143], v[194:195]
	global_load_dwordx4 v[192:195], v189, s[16:17] offset:1024
	s_waitcnt vmcnt(14)
	v_pk_add_f32 v[140:141], v[140:141], v[196:197]
	v_pk_add_f32 v[142:143], v[142:143], v[198:199]
	global_load_dwordx4 v[196:199], v189, s[88:89] offset:1024
	s_waitcnt vmcnt(14)
	v_pk_add_f32 v[140:141], v[140:141], v[200:201]
	v_pk_add_f32 v[142:143], v[142:143], v[202:203]
	global_load_dwordx4 v[200:203], v189, s[90:91] offset:1024
	s_waitcnt vmcnt(14)
	v_pk_add_f32 v[136:137], v[136:137], v[204:205]
	v_pk_add_f32 v[138:139], v[138:139], v[206:207]
	global_load_dwordx4 v[204:207], v189, s[16:17] offset:2048
	s_waitcnt vmcnt(14)
	v_pk_add_f32 v[136:137], v[136:137], v[208:209]
	v_pk_add_f32 v[138:139], v[138:139], v[210:211]
	global_load_dwordx4 v[208:211], v189, s[88:89] offset:2048
	s_waitcnt vmcnt(14)
	v_pk_add_f32 v[136:137], v[136:137], v[212:213]
	v_pk_add_f32 v[138:139], v[138:139], v[214:215]
	global_load_dwordx4 v[212:215], v189, s[90:91] offset:2048
	s_waitcnt vmcnt(14)
	v_pk_add_f32 v[132:133], v[132:133], v[216:217]
	v_pk_add_f32 v[134:135], v[134:135], v[218:219]
	global_load_dwordx4 v[216:219], v189, s[16:17] offset:3072
	s_waitcnt vmcnt(14)
	v_pk_add_f32 v[132:133], v[132:133], v[220:221]
	v_pk_add_f32 v[134:135], v[134:135], v[222:223]
	global_load_dwordx4 v[220:223], v189, s[88:89] offset:3072
	s_waitcnt vmcnt(14)
	v_pk_add_f32 v[132:133], v[132:133], v[224:225]
	v_pk_add_f32 v[134:135], v[134:135], v[226:227]
	global_load_dwordx4 v[224:227], v189, s[90:91] offset:3072
	s_waitcnt vmcnt(14)
	v_pk_add_f32 v[128:129], v[128:129], v[228:229]
	v_pk_add_f32 v[130:131], v[130:131], v[230:231]
	s_add_u32 s16, s16, 0x1000
	s_addc_u32 s17, s17, 0
	s_add_u32 s88, s88, 0x1000
	s_addc_u32 s89, s89, 0
	s_add_u32 s90, s90, 0x1000
	s_addc_u32 s91, s91, 0
	global_load_dwordx4 v[228:231], v189, s[16:17]
	s_waitcnt vmcnt(14)
	v_pk_add_f32 v[128:129], v[128:129], v[232:233]
	v_pk_add_f32 v[130:131], v[130:131], v[234:235]
	global_load_dwordx4 v[232:235], v189, s[88:89]
	s_waitcnt vmcnt(14)
	v_pk_add_f32 v[128:129], v[128:129], v[84:85]
	v_pk_add_f32 v[130:131], v[130:131], v[86:87]
	global_load_dwordx4 v[84:87], v189, s[90:91]
	s_waitcnt vmcnt(14)
	v_pk_add_f32 v[124:125], v[124:125], v[88:89]
	v_pk_add_f32 v[126:127], v[126:127], v[90:91]
	global_load_dwordx4 v[88:91], v189, s[16:17] offset:1024
	s_waitcnt vmcnt(14)
	v_pk_add_f32 v[124:125], v[124:125], v[76:77]
	v_pk_add_f32 v[126:127], v[126:127], v[78:79]
	global_load_dwordx4 v[76:79], v189, s[88:89] offset:1024
	s_waitcnt vmcnt(14)
	v_pk_add_f32 v[124:125], v[124:125], v[96:97]
	v_pk_add_f32 v[126:127], v[126:127], v[98:99]
	global_load_dwordx4 v[96:99], v189, s[90:91] offset:1024
	s_waitcnt vmcnt(14)
	v_pk_add_f32 v[120:121], v[120:121], v[192:193]
	v_pk_add_f32 v[122:123], v[122:123], v[194:195]
	global_load_dwordx4 v[192:195], v189, s[16:17] offset:2048
	s_waitcnt vmcnt(14)
	v_pk_add_f32 v[120:121], v[120:121], v[196:197]
	v_pk_add_f32 v[122:123], v[122:123], v[198:199]
	global_load_dwordx4 v[196:199], v189, s[88:89] offset:2048
	s_waitcnt vmcnt(14)
	v_pk_add_f32 v[120:121], v[120:121], v[200:201]
	v_pk_add_f32 v[122:123], v[122:123], v[202:203]
	global_load_dwordx4 v[200:203], v189, s[90:91] offset:2048
	s_waitcnt vmcnt(14)
	v_pk_add_f32 v[116:117], v[116:117], v[204:205]
	v_pk_add_f32 v[118:119], v[118:119], v[206:207]
	global_load_dwordx4 v[204:207], v189, s[16:17] offset:3072
	s_waitcnt vmcnt(14)
	v_pk_add_f32 v[116:117], v[116:117], v[208:209]
	v_pk_add_f32 v[118:119], v[118:119], v[210:211]
	global_load_dwordx4 v[208:211], v189, s[88:89] offset:3072
	s_waitcnt vmcnt(14)
	v_pk_add_f32 v[116:117], v[116:117], v[212:213]
	v_pk_add_f32 v[118:119], v[118:119], v[214:215]
	global_load_dwordx4 v[212:215], v189, s[90:91] offset:3072
	s_waitcnt vmcnt(14)
	v_pk_add_f32 v[112:113], v[112:113], v[216:217]
	v_pk_add_f32 v[114:115], v[114:115], v[218:219]
	s_add_u32 s16, s16, 0x1000
	s_addc_u32 s17, s17, 0
	s_add_u32 s88, s88, 0x1000
	s_addc_u32 s89, s89, 0
	s_add_u32 s90, s90, 0x1000
	s_addc_u32 s91, s91, 0
	global_load_dwordx4 v[216:219], v189, s[16:17]
	s_waitcnt vmcnt(14)
	v_pk_add_f32 v[112:113], v[112:113], v[220:221]
	v_pk_add_f32 v[114:115], v[114:115], v[222:223]
	global_load_dwordx4 v[220:223], v189, s[88:89]
	s_waitcnt vmcnt(14)
	v_pk_add_f32 v[112:113], v[112:113], v[224:225]
	v_pk_add_f32 v[114:115], v[114:115], v[226:227]
	global_load_dwordx4 v[224:227], v189, s[90:91]
	s_waitcnt vmcnt(14)
	v_pk_add_f32 v[108:109], v[108:109], v[228:229]
	v_pk_add_f32 v[110:111], v[110:111], v[230:231]
	global_load_dwordx4 v[228:231], v189, s[16:17] offset:1024
	s_waitcnt vmcnt(14)
	v_pk_add_f32 v[108:109], v[108:109], v[232:233]
	v_pk_add_f32 v[110:111], v[110:111], v[234:235]
	global_load_dwordx4 v[232:235], v189, s[88:89] offset:1024
	s_waitcnt vmcnt(14)
	v_pk_add_f32 v[108:109], v[108:109], v[84:85]
	v_pk_add_f32 v[110:111], v[110:111], v[86:87]
	global_load_dwordx4 v[84:87], v189, s[90:91] offset:1024
	s_waitcnt vmcnt(14)
	v_pk_add_f32 v[104:105], v[104:105], v[88:89]
	v_pk_add_f32 v[106:107], v[106:107], v[90:91]
	global_load_dwordx4 v[88:91], v189, s[16:17] offset:2048
	s_waitcnt vmcnt(14)
	v_pk_add_f32 v[104:105], v[104:105], v[76:77]
	v_pk_add_f32 v[106:107], v[106:107], v[78:79]
	global_load_dwordx4 v[76:79], v189, s[88:89] offset:2048
	s_waitcnt vmcnt(14)
	v_pk_add_f32 v[104:105], v[104:105], v[96:97]
	v_pk_add_f32 v[106:107], v[106:107], v[98:99]
	global_load_dwordx4 v[96:99], v189, s[90:91] offset:2048
	s_waitcnt vmcnt(14)
	v_pk_add_f32 v[100:101], v[100:101], v[192:193]
	v_pk_add_f32 v[102:103], v[102:103], v[194:195]
	global_load_dwordx4 v[192:195], v189, s[16:17] offset:3072
	s_waitcnt vmcnt(14)
	v_pk_add_f32 v[100:101], v[100:101], v[196:197]
	v_pk_add_f32 v[102:103], v[102:103], v[198:199]
	global_load_dwordx4 v[196:199], v189, s[88:89] offset:3072
	s_waitcnt vmcnt(14)
	v_pk_add_f32 v[100:101], v[100:101], v[200:201]
	v_pk_add_f32 v[102:103], v[102:103], v[202:203]
	global_load_dwordx4 v[200:203], v189, s[90:91] offset:3072
	s_waitcnt vmcnt(14)
	v_pk_add_f32 v[92:93], v[92:93], v[204:205]
	v_pk_add_f32 v[94:95], v[94:95], v[206:207]
	s_add_u32 s16, s16, 0x1000
	s_addc_u32 s17, s17, 0
	s_add_u32 s88, s88, 0x1000
	s_addc_u32 s89, s89, 0
	s_add_u32 s90, s90, 0x1000
	s_addc_u32 s91, s91, 0
	global_load_dwordx4 v[204:207], v189, s[16:17]
	s_waitcnt vmcnt(14)
	v_pk_add_f32 v[92:93], v[92:93], v[208:209]
	v_pk_add_f32 v[94:95], v[94:95], v[210:211]
	global_load_dwordx4 v[208:211], v189, s[88:89]
	s_waitcnt vmcnt(14)
	v_pk_add_f32 v[92:93], v[92:93], v[212:213]
	v_pk_add_f32 v[94:95], v[94:95], v[214:215]
	global_load_dwordx4 v[212:215], v189, s[90:91]
	s_waitcnt vmcnt(14)
	v_pk_add_f32 v[80:81], v[80:81], v[216:217]
	v_pk_add_f32 v[82:83], v[82:83], v[218:219]
	global_load_dwordx4 v[216:219], v189, s[16:17] offset:1024
	s_waitcnt vmcnt(14)
	v_pk_add_f32 v[80:81], v[80:81], v[220:221]
	v_pk_add_f32 v[82:83], v[82:83], v[222:223]
	global_load_dwordx4 v[220:223], v189, s[88:89] offset:1024
	s_waitcnt vmcnt(14)
	v_pk_add_f32 v[80:81], v[80:81], v[224:225]
	v_pk_add_f32 v[82:83], v[82:83], v[226:227]
	global_load_dwordx4 v[224:227], v189, s[90:91] offset:1024
	s_waitcnt vmcnt(14)
	v_pk_add_f32 v[72:73], v[72:73], v[228:229]
	v_pk_add_f32 v[74:75], v[74:75], v[230:231]
	global_load_dwordx4 v[228:231], v189, s[16:17] offset:2048
	s_waitcnt vmcnt(14)
	v_pk_add_f32 v[72:73], v[72:73], v[232:233]
	v_pk_add_f32 v[74:75], v[74:75], v[234:235]
	global_load_dwordx4 v[232:235], v189, s[88:89] offset:2048
	s_waitcnt vmcnt(14)
	v_pk_add_f32 v[72:73], v[72:73], v[84:85]
	v_pk_add_f32 v[74:75], v[74:75], v[86:87]
	global_load_dwordx4 v[84:87], v189, s[90:91] offset:2048
	s_waitcnt vmcnt(14)
	v_pk_add_f32 v[68:69], v[68:69], v[88:89]
	v_pk_add_f32 v[70:71], v[70:71], v[90:91]
	global_load_dwordx4 v[88:91], v189, s[16:17] offset:3072
	s_waitcnt vmcnt(14)
	v_pk_add_f32 v[68:69], v[68:69], v[76:77]
	v_pk_add_f32 v[70:71], v[70:71], v[78:79]
	global_load_dwordx4 v[76:79], v189, s[88:89] offset:3072
	s_waitcnt vmcnt(14)
	v_pk_add_f32 v[68:69], v[68:69], v[96:97]
	v_pk_add_f32 v[70:71], v[70:71], v[98:99]
	global_load_dwordx4 v[96:99], v189, s[90:91] offset:3072
	s_waitcnt vmcnt(14)
	v_pk_add_f32 v[64:65], v[64:65], v[192:193]
	v_pk_add_f32 v[66:67], v[66:67], v[194:195]
	s_add_u32 s16, s16, 0x1000
	s_addc_u32 s17, s17, 0
	s_add_u32 s88, s88, 0x1000
	s_addc_u32 s89, s89, 0
	s_add_u32 s90, s90, 0x1000
	s_addc_u32 s91, s91, 0
	global_load_dwordx4 v[192:195], v189, s[16:17]
	s_waitcnt vmcnt(14)
	v_pk_add_f32 v[64:65], v[64:65], v[196:197]
	v_pk_add_f32 v[66:67], v[66:67], v[198:199]
	global_load_dwordx4 v[196:199], v189, s[88:89]
	s_waitcnt vmcnt(14)
	v_pk_add_f32 v[64:65], v[64:65], v[200:201]
	v_pk_add_f32 v[66:67], v[66:67], v[202:203]
	global_load_dwordx4 v[200:203], v189, s[90:91]
	s_waitcnt vmcnt(14)
	v_pk_add_f32 v[60:61], v[60:61], v[204:205]
	v_pk_add_f32 v[62:63], v[62:63], v[206:207]
	global_load_dwordx4 v[204:207], v189, s[16:17] offset:1024
	s_waitcnt vmcnt(14)
	v_pk_add_f32 v[60:61], v[60:61], v[208:209]
	v_pk_add_f32 v[62:63], v[62:63], v[210:211]
	global_load_dwordx4 v[208:211], v189, s[88:89] offset:1024
	s_waitcnt vmcnt(14)
	v_pk_add_f32 v[60:61], v[60:61], v[212:213]
	v_pk_add_f32 v[62:63], v[62:63], v[214:215]
	global_load_dwordx4 v[212:215], v189, s[90:91] offset:1024
	s_waitcnt vmcnt(14)
	v_pk_add_f32 v[56:57], v[56:57], v[216:217]
	v_pk_add_f32 v[58:59], v[58:59], v[218:219]
	global_load_dwordx4 v[216:219], v189, s[16:17] offset:2048
	s_waitcnt vmcnt(14)
	v_pk_add_f32 v[56:57], v[56:57], v[220:221]
	v_pk_add_f32 v[58:59], v[58:59], v[222:223]
	global_load_dwordx4 v[220:223], v189, s[88:89] offset:2048
	s_waitcnt vmcnt(14)
	v_pk_add_f32 v[56:57], v[56:57], v[224:225]
	v_pk_add_f32 v[58:59], v[58:59], v[226:227]
	global_load_dwordx4 v[224:227], v189, s[90:91] offset:2048
	s_waitcnt vmcnt(14)
	v_pk_add_f32 v[52:53], v[52:53], v[228:229]
	v_pk_add_f32 v[54:55], v[54:55], v[230:231]
	global_load_dwordx4 v[228:231], v189, s[16:17] offset:3072
	s_waitcnt vmcnt(14)
	v_pk_add_f32 v[52:53], v[52:53], v[232:233]
	v_pk_add_f32 v[54:55], v[54:55], v[234:235]
	global_load_dwordx4 v[232:235], v189, s[88:89] offset:3072
	s_waitcnt vmcnt(14)
	v_pk_add_f32 v[52:53], v[52:53], v[84:85]
	v_pk_add_f32 v[54:55], v[54:55], v[86:87]
	global_load_dwordx4 v[84:87], v189, s[90:91] offset:3072
	s_waitcnt vmcnt(14)
	v_pk_add_f32 v[48:49], v[48:49], v[88:89]
	v_pk_add_f32 v[50:51], v[50:51], v[90:91]
	s_add_u32 s16, s16, 0x1000
	s_addc_u32 s17, s17, 0
	s_add_u32 s88, s88, 0x1000
	s_addc_u32 s89, s89, 0
	s_add_u32 s90, s90, 0x1000
	s_addc_u32 s91, s91, 0
	global_load_dwordx4 v[88:91], v189, s[16:17]
	s_waitcnt vmcnt(14)
	v_pk_add_f32 v[48:49], v[48:49], v[76:77]
	v_pk_add_f32 v[50:51], v[50:51], v[78:79]
	global_load_dwordx4 v[76:79], v189, s[88:89]
	s_waitcnt vmcnt(14)
	v_pk_add_f32 v[48:49], v[48:49], v[96:97]
	v_pk_add_f32 v[50:51], v[50:51], v[98:99]
	global_load_dwordx4 v[96:99], v189, s[90:91]
	s_waitcnt vmcnt(14)
	v_pk_add_f32 v[44:45], v[44:45], v[192:193]
	v_pk_add_f32 v[46:47], v[46:47], v[194:195]
	global_load_dwordx4 v[192:195], v189, s[16:17] offset:1024
	s_waitcnt vmcnt(14)
	v_pk_add_f32 v[44:45], v[44:45], v[196:197]
	v_pk_add_f32 v[46:47], v[46:47], v[198:199]
	global_load_dwordx4 v[196:199], v189, s[88:89] offset:1024
	s_waitcnt vmcnt(14)
	v_pk_add_f32 v[44:45], v[44:45], v[200:201]
	v_pk_add_f32 v[46:47], v[46:47], v[202:203]
	global_load_dwordx4 v[200:203], v189, s[90:91] offset:1024
	s_waitcnt vmcnt(14)
	v_pk_add_f32 v[40:41], v[40:41], v[204:205]
	v_pk_add_f32 v[42:43], v[42:43], v[206:207]
	global_load_dwordx4 v[204:207], v189, s[16:17] offset:2048
	s_waitcnt vmcnt(14)
	v_pk_add_f32 v[40:41], v[40:41], v[208:209]
	v_pk_add_f32 v[42:43], v[42:43], v[210:211]
	global_load_dwordx4 v[208:211], v189, s[88:89] offset:2048
	s_waitcnt vmcnt(14)
	v_pk_add_f32 v[40:41], v[40:41], v[212:213]
	v_pk_add_f32 v[42:43], v[42:43], v[214:215]
	global_load_dwordx4 v[212:215], v189, s[90:91] offset:2048
	s_waitcnt vmcnt(14)
	v_pk_add_f32 v[36:37], v[36:37], v[216:217]
	v_pk_add_f32 v[38:39], v[38:39], v[218:219]
	global_load_dwordx4 v[216:219], v189, s[16:17] offset:3072
	s_waitcnt vmcnt(14)
	v_pk_add_f32 v[36:37], v[36:37], v[220:221]
	v_pk_add_f32 v[38:39], v[38:39], v[222:223]
	global_load_dwordx4 v[220:223], v189, s[88:89] offset:3072
	s_waitcnt vmcnt(14)
	v_pk_add_f32 v[36:37], v[36:37], v[224:225]
	v_pk_add_f32 v[38:39], v[38:39], v[226:227]
	global_load_dwordx4 v[224:227], v189, s[90:91] offset:3072
	s_waitcnt vmcnt(14)
	v_pk_add_f32 v[32:33], v[32:33], v[228:229]
	v_pk_add_f32 v[34:35], v[34:35], v[230:231]
	s_add_u32 s16, s16, 0x1000
	s_addc_u32 s17, s17, 0
	s_add_u32 s88, s88, 0x1000
	s_addc_u32 s89, s89, 0
	s_add_u32 s90, s90, 0x1000
	s_addc_u32 s91, s91, 0
	global_load_dwordx4 v[228:231], v189, s[16:17]
	s_waitcnt vmcnt(14)
	v_pk_add_f32 v[32:33], v[32:33], v[232:233]
	v_pk_add_f32 v[34:35], v[34:35], v[234:235]
	global_load_dwordx4 v[232:235], v189, s[88:89]
	s_waitcnt vmcnt(14)
	v_pk_add_f32 v[32:33], v[32:33], v[84:85]
	v_pk_add_f32 v[34:35], v[34:35], v[86:87]
	global_load_dwordx4 v[84:87], v189, s[90:91]
	s_waitcnt vmcnt(14)
	v_pk_add_f32 v[28:29], v[28:29], v[88:89]
	v_pk_add_f32 v[30:31], v[30:31], v[90:91]
	global_load_dwordx4 v[88:91], v189, s[16:17] offset:1024
	s_waitcnt vmcnt(14)
	v_pk_add_f32 v[28:29], v[28:29], v[76:77]
	v_pk_add_f32 v[30:31], v[30:31], v[78:79]
	global_load_dwordx4 v[76:79], v189, s[88:89] offset:1024
	s_waitcnt vmcnt(14)
	v_pk_add_f32 v[28:29], v[28:29], v[96:97]
	v_pk_add_f32 v[30:31], v[30:31], v[98:99]
	global_load_dwordx4 v[96:99], v189, s[90:91] offset:1024
	s_waitcnt vmcnt(14)
	v_pk_add_f32 v[24:25], v[24:25], v[192:193]
	v_pk_add_f32 v[26:27], v[26:27], v[194:195]
	global_load_dwordx4 v[192:195], v189, s[16:17] offset:2048
	s_waitcnt vmcnt(14)
	v_pk_add_f32 v[24:25], v[24:25], v[196:197]
	v_pk_add_f32 v[26:27], v[26:27], v[198:199]
	global_load_dwordx4 v[196:199], v189, s[88:89] offset:2048
	s_waitcnt vmcnt(14)
	v_pk_add_f32 v[24:25], v[24:25], v[200:201]
	v_pk_add_f32 v[26:27], v[26:27], v[202:203]
	global_load_dwordx4 v[200:203], v189, s[90:91] offset:2048
	s_waitcnt vmcnt(14)
	v_pk_add_f32 v[20:21], v[20:21], v[204:205]
	v_pk_add_f32 v[22:23], v[22:23], v[206:207]
	global_load_dwordx4 v[204:207], v189, s[16:17] offset:3072
	s_waitcnt vmcnt(14)
	v_pk_add_f32 v[20:21], v[20:21], v[208:209]
	v_pk_add_f32 v[22:23], v[22:23], v[210:211]
	global_load_dwordx4 v[208:211], v189, s[88:89] offset:3072
	s_waitcnt vmcnt(14)
	v_pk_add_f32 v[20:21], v[20:21], v[212:213]
	v_pk_add_f32 v[22:23], v[22:23], v[214:215]
	global_load_dwordx4 v[212:215], v189, s[90:91] offset:3072
	s_waitcnt vmcnt(14)
	v_pk_add_f32 v[16:17], v[16:17], v[216:217]
	v_pk_add_f32 v[18:19], v[18:19], v[218:219]
	s_waitcnt vmcnt(13)
	v_pk_add_f32 v[16:17], v[16:17], v[220:221]
	v_pk_add_f32 v[18:19], v[18:19], v[222:223]
	s_waitcnt vmcnt(12)
	v_pk_add_f32 v[16:17], v[16:17], v[224:225]
	v_pk_add_f32 v[18:19], v[18:19], v[226:227]
	s_waitcnt vmcnt(11)
	v_pk_add_f32 v[12:13], v[12:13], v[228:229]
	v_pk_add_f32 v[14:15], v[14:15], v[230:231]
	s_waitcnt vmcnt(10)
	v_pk_add_f32 v[12:13], v[12:13], v[232:233]
	v_pk_add_f32 v[14:15], v[14:15], v[234:235]
	s_waitcnt vmcnt(9)
	v_pk_add_f32 v[12:13], v[12:13], v[84:85]
	v_pk_add_f32 v[14:15], v[14:15], v[86:87]
	s_waitcnt vmcnt(8)
	v_pk_add_f32 v[8:9], v[8:9], v[88:89]
	v_pk_add_f32 v[10:11], v[10:11], v[90:91]
	s_waitcnt vmcnt(7)
	v_pk_add_f32 v[8:9], v[8:9], v[76:77]
	v_pk_add_f32 v[10:11], v[10:11], v[78:79]
	s_waitcnt vmcnt(6)
	v_pk_add_f32 v[8:9], v[8:9], v[96:97]
	v_pk_add_f32 v[10:11], v[10:11], v[98:99]
	s_waitcnt vmcnt(5)
	v_pk_add_f32 v[4:5], v[4:5], v[192:193]
	v_pk_add_f32 v[6:7], v[6:7], v[194:195]
	s_waitcnt vmcnt(4)
	v_pk_add_f32 v[4:5], v[4:5], v[196:197]
	v_pk_add_f32 v[6:7], v[6:7], v[198:199]
	s_waitcnt vmcnt(3)
	v_pk_add_f32 v[4:5], v[4:5], v[200:201]
	v_pk_add_f32 v[6:7], v[6:7], v[202:203]
	s_waitcnt vmcnt(2)
	v_pk_add_f32 v[0:1], v[0:1], v[204:205]
	v_pk_add_f32 v[2:3], v[2:3], v[206:207]
	s_waitcnt vmcnt(1)
	v_pk_add_f32 v[0:1], v[0:1], v[208:209]
	v_pk_add_f32 v[2:3], v[2:3], v[210:211]
	s_waitcnt vmcnt(0)
	v_pk_add_f32 v[0:1], v[0:1], v[212:213]
	v_pk_add_f32 v[2:3], v[2:3], v[214:215]
